# retention-output (Ynorm) stores coalesced the same way: per-wave LDS transpose (the V tile region is dead after the norm barrier), 8 stores each writing 4 rows x 256 B of full cache lines
# speedup vs baseline: 1.0160x; 1.0056x over previous
; #define LAS __attribute__((address_space(3)))
; __device__ void ret_out_item(const bf16_t* __restrict__ Qb, const bf16_t* __restrict__ Kb, bf16_t* Vb, const bf16_t* __restrict__ STf, const bf16_t* __restrict__ STb,
;                              int cidx, int head, float lgf2, float lgb2, LAS unsigned char* lds) {
;     ...
;   ss += __shfl_xor(ss, 32);
;   LAS float* red = (LAS float*)(lds + ORED);
;   if (h == 0) red[eh * 128 + iloc] = ss;
;   __syncthreads();
.LBB0_623:
	s_or_b64 exec, exec, s[34:35]
	v_lshl_add_u32 v64, v147, 2, 0
	v_add_u32_e32 v64, 0x12000, v64
	s_waitcnt lgkmcnt(0)
	s_barrier
; __device__ __forceinline__ u32x2 pack4(float a, float b, float c, float d) { u32x2 o; o[0] = cvt_pk_bf16(a, b); o[1] = cvt_pk_bf16(c, d); return o; }
; __device__ __forceinline__ void store_tile16(bf16_t* p, const f32x16& a, float sc, int h) {
; #pragma unroll
;   for (int gp = 0; gp < 2; ++gp) {
;     u32x2 A = pack4(a[8 * gp] * sc, a[8 * gp + 1] * sc, a[8 * gp + 2] * sc, a[8 * gp + 3] * sc), B = pack4(a[8 * gp + 4] * sc, a[8 * gp + 5] * sc, a[8 * gp + 6] * sc, a[8 * gp + 7] * sc);
;     const auto r0 = __builtin_amdgcn_permlane32_swap(A[0], B[0], false, false), r1 = __builtin_amdgcn_permlane32_swap(A[1], B[1], false, false);
;     u32x4 o = {r0[0], r1[0], r0[1], r1[1]};
;     *(u32x4*)(p + 16 * gp + 8 * h) = o;
; __device__ void ret_out_item(const bf16_t* __restrict__ Qb, const bf16_t* __restrict__ Kb, bf16_t* Vb, const bf16_t* __restrict__ STf, const bf16_t* __restrict__ STb,
;                              int cidx, int head, float lgf2, float lgb2, LAS unsigned char* lds) {
;     ...
;   const float rn = rsqrtf((red[iloc] + red[128 + iloc]) * (1.f / 256.f) + 1e-6f);
;   bf16_t* op = Vb + (size_t)(row0 + iloc) * 1024 + head * 256 + eh * 128;
; #pragma unroll
;   for (int et = 0; et < 4; ++et) store_tile16(op + et * 32, acc[et], rn, h);
;   __syncthreads();
	ds_read2st64_b32 v[64:65], v64 offset1:2
	s_mov_b32 s20, 0x800000
	v_lshlrev_b32_e32 v67, 3, v146
	v_lshlrev_b32_e32 v160, 1, v67
	s_add_i32 s7, s7, s90
	s_waitcnt lgkmcnt(0)
	v_add_f32_e32 v64, v64, v65
	v_fmamk_f32 v64, v64, 0x3b800000, v217
	v_mul_f32_e32 v65, 0x4b800000, v64
	v_cmp_gt_f32_e32 vcc, s20, v64
	s_lshl_b32 s20, s12, 1
	v_readlane_b32 s12, v255, 34
	v_cndmask_b32_e32 v64, v64, v65, vcc
	v_rsq_f32_e32 v66, v64
	v_or_b32_e32 v64, s13, v147
	v_ashrrev_i32_e32 v65, 31, v64
	v_lshlrev_b64 v[64:65], 11, v[64:65]
	v_mul_f32_e32 v68, 0x45800000, v66
	v_cndmask_b32_e32 v66, v66, v68, vcc
	v_lshl_add_u64 v[64:65], s[14:15], 0, v[64:65]
	v_pk_mul_f32 v[48:49], v[48:49], v[66:67] op_sel_hi:[1,0]
	v_pk_mul_f32 v[50:51], v[50:51], v[66:67] op_sel_hi:[1,0]
	v_pk_mul_f32 v[32:33], v[32:33], v[66:67] op_sel_hi:[1,0]
	v_pk_mul_f32 v[34:35], v[34:35], v[66:67] op_sel_hi:[1,0]
	v_pk_mul_f32 v[16:17], v[16:17], v[66:67] op_sel_hi:[1,0]
	v_pk_mul_f32 v[18:19], v[18:19], v[66:67] op_sel_hi:[1,0]
	v_pk_mul_f32 v[0:1], v[0:1], v[66:67] op_sel_hi:[1,0]
	v_pk_mul_f32 v[2:3], v[2:3], v[66:67] op_sel_hi:[1,0]
	v_lshl_add_u64 v[64:65], v[64:65], 0, s[20:21]
	v_cvt_pk_bf16_f32 v48, v48, v49
	v_cvt_pk_bf16_f32 v49, v50, v51
	v_pk_mul_f32 v[50:51], v[52:53], v[66:67] op_sel_hi:[1,0]
	v_pk_mul_f32 v[52:53], v[54:55], v[66:67] op_sel_hi:[1,0]
	v_cvt_pk_bf16_f32 v32, v32, v33
	v_cvt_pk_bf16_f32 v33, v34, v35
	v_pk_mul_f32 v[34:35], v[36:37], v[66:67] op_sel_hi:[1,0]
	v_pk_mul_f32 v[36:37], v[38:39], v[66:67] op_sel_hi:[1,0]
	v_cvt_pk_bf16_f32 v16, v16, v17
	v_cvt_pk_bf16_f32 v17, v18, v19
	v_pk_mul_f32 v[18:19], v[20:21], v[66:67] op_sel_hi:[1,0]
	v_pk_mul_f32 v[20:21], v[22:23], v[66:67] op_sel_hi:[1,0]
	v_cvt_pk_bf16_f32 v0, v0, v1
	v_cvt_pk_bf16_f32 v1, v2, v3
	v_pk_mul_f32 v[2:3], v[4:5], v[66:67] op_sel_hi:[1,0]
	v_pk_mul_f32 v[4:5], v[6:7], v[66:67] op_sel_hi:[1,0]
	v_lshl_add_u64 v[64:65], v[136:137], 1, v[64:65]
	v_cvt_pk_bf16_f32 v50, v50, v51
	v_cvt_pk_bf16_f32 v51, v52, v53
	v_cvt_pk_bf16_f32 v34, v34, v35
	v_cvt_pk_bf16_f32 v35, v36, v37
	v_cvt_pk_bf16_f32 v18, v18, v19
	v_cvt_pk_bf16_f32 v19, v20, v21
	v_cvt_pk_bf16_f32 v2, v2, v3
	v_cvt_pk_bf16_f32 v3, v4, v5
	v_lshl_add_u64 v[64:65], v[64:65], 0, v[160:161]
	v_permlane32_swap_b32_e32 v48, v50
	v_permlane32_swap_b32_e32 v49, v51
	v_permlane32_swap_b32_e32 v32, v34
	v_permlane32_swap_b32_e32 v33, v35
	v_permlane32_swap_b32_e32 v16, v18
	v_permlane32_swap_b32_e32 v17, v19
	v_permlane32_swap_b32_e32 v0, v2
	v_permlane32_swap_b32_e32 v1, v3
	v_lshrrev_b32_e32 v210, 6, v214
	v_mul_u32_u24_e32 v210, 0x2200, v210
	v_and_b32_e32 v211, 63, v214
	v_lshrrev_b32_e32 v208, 4, v211
	v_mul_u32_u24_e32 v208, 0x110, v208
	v_and_b32_e32 v209, 15, v211
	v_lshl_add_u32 v208, v209, 4, v208
	v_add_u32_e32 v211, v210, v208
	v_and_b32_e32 v208, 31, v214
	v_mul_u32_u24_e32 v208, 0x110, v208
	v_bfe_u32 v209, v214, 5, 1
	v_lshl_add_u32 v208, v209, 4, v208
	v_add_u32_e32 v210, v210, v208
	ds_write_b128 v210, v[48:51]
	ds_write_b128 v210, v[32:35] offset:64
	ds_write_b128 v210, v[16:19] offset:128
	v_pk_mul_f32 v[48:49], v[56:57], v[66:67] op_sel_hi:[1,0]
	v_pk_mul_f32 v[50:51], v[58:59], v[66:67] op_sel_hi:[1,0]
	v_pk_mul_f32 v[32:33], v[40:41], v[66:67] op_sel_hi:[1,0]
	v_pk_mul_f32 v[34:35], v[42:43], v[66:67] op_sel_hi:[1,0]
	v_pk_mul_f32 v[16:17], v[24:25], v[66:67] op_sel_hi:[1,0]
	v_pk_mul_f32 v[18:19], v[26:27], v[66:67] op_sel_hi:[1,0]
	ds_write_b128 v210, v[0:3] offset:192
	s_add_i32 s6, s6, s12
	v_readlane_b32 s12, v255, 40
	v_pk_mul_f32 v[0:1], v[8:9], v[66:67] op_sel_hi:[1,0]
	v_pk_mul_f32 v[2:3], v[10:11], v[66:67] op_sel_hi:[1,0]
	v_cvt_pk_bf16_f32 v48, v48, v49
	v_cvt_pk_bf16_f32 v49, v50, v51
	v_pk_mul_f32 v[50:51], v[60:61], v[66:67] op_sel_hi:[1,0]
	v_pk_mul_f32 v[52:53], v[62:63], v[66:67] op_sel_hi:[1,0]
	v_cvt_pk_bf16_f32 v32, v32, v33
	v_cvt_pk_bf16_f32 v33, v34, v35
	v_pk_mul_f32 v[34:35], v[44:45], v[66:67] op_sel_hi:[1,0]
	v_pk_mul_f32 v[36:37], v[46:47], v[66:67] op_sel_hi:[1,0]
	v_cvt_pk_bf16_f32 v16, v16, v17
	v_cvt_pk_bf16_f32 v17, v18, v19
	v_pk_mul_f32 v[18:19], v[28:29], v[66:67] op_sel_hi:[1,0]
	v_pk_mul_f32 v[20:21], v[30:31], v[66:67] op_sel_hi:[1,0]
	v_cvt_pk_bf16_f32 v0, v0, v1
	v_cvt_pk_bf16_f32 v1, v2, v3
	v_pk_mul_f32 v[2:3], v[12:13], v[66:67] op_sel_hi:[1,0]
	v_pk_mul_f32 v[4:5], v[14:15], v[66:67] op_sel_hi:[1,0]
	v_readlane_b32 s13, v255, 41
	s_add_u32 s22, s22, s12
	v_cvt_pk_bf16_f32 v50, v50, v51
	v_cvt_pk_bf16_f32 v51, v52, v53
	v_cvt_pk_bf16_f32 v34, v34, v35
	v_cvt_pk_bf16_f32 v35, v36, v37
	v_cvt_pk_bf16_f32 v18, v18, v19
	v_cvt_pk_bf16_f32 v19, v20, v21
	v_cvt_pk_bf16_f32 v2, v2, v3
	v_cvt_pk_bf16_f32 v3, v4, v5
	s_addc_u32 s23, s23, s13
	v_permlane32_swap_b32_e32 v48, v50
	v_permlane32_swap_b32_e32 v49, v51
	v_permlane32_swap_b32_e32 v32, v34
	v_permlane32_swap_b32_e32 v33, v35
	v_permlane32_swap_b32_e32 v16, v18
	v_permlane32_swap_b32_e32 v17, v19
	v_permlane32_swap_b32_e32 v0, v2
	v_permlane32_swap_b32_e32 v1, v3
	s_cmpk_gt_i32 s7, 0x3ff
	ds_write_b128 v210, v[48:51] offset:32
	ds_write_b128 v210, v[32:35] offset:96
	ds_write_b128 v210, v[16:19] offset:160
	ds_write_b128 v210, v[0:3] offset:224
	s_waitcnt lgkmcnt(0)
	v_and_b32_e32 v208, 63, v214
	v_lshrrev_b32_e32 v209, 4, v208
	v_lshlrev_b32_e32 v209, 11, v209
	v_and_b32_e32 v208, 15, v208
	v_lshl_add_u32 v208, v208, 4, v209
	v_and_b32_e32 v209, 31, v214
	v_lshlrev_b32_e32 v209, 11, v209
	v_sub_u32_e32 v208, v208, v209
	v_bfe_u32 v209, v214, 5, 1
	v_lshlrev_b32_e32 v209, 4, v209
	v_sub_u32_e32 v208, v208, v209
	v_ashrrev_i32_e32 v209, 31, v208
	v_lshl_add_u64 v[206:207], v[64:65], 0, v[208:209]
	s_mov_b32 s38, 0x2000
	s_mov_b32 s39, 0
	v_lshl_add_u64 v[208:209], v[206:207], 0, s[38:39]
	s_mov_b32 s38, 0x4000
	ds_read_b128 v[0:3], v211
	ds_read_b128 v[4:7], v211 offset:1088
	ds_read_b128 v[8:11], v211 offset:2176
	ds_read_b128 v[12:15], v211 offset:3264
	ds_read_b128 v[16:19], v211 offset:4352
	ds_read_b128 v[20:23], v211 offset:5440
	ds_read_b128 v[24:27], v211 offset:6528
	ds_read_b128 v[28:31], v211 offset:7616
	s_waitcnt lgkmcnt(7)
	global_store_dwordx4 v[206:207], v[0:3], off
	s_waitcnt lgkmcnt(6)
	global_store_dwordx4 v[208:209], v[4:7], off
	s_nop 1
	v_lshl_add_u64 v[206:207], v[206:207], 0, s[38:39]
	v_lshl_add_u64 v[208:209], v[208:209], 0, s[38:39]
	s_waitcnt lgkmcnt(5)
	global_store_dwordx4 v[206:207], v[8:11], off
	s_waitcnt lgkmcnt(4)
	global_store_dwordx4 v[208:209], v[12:15], off
	s_nop 1
	v_lshl_add_u64 v[206:207], v[206:207], 0, s[38:39]
	v_lshl_add_u64 v[208:209], v[208:209], 0, s[38:39]
	s_waitcnt lgkmcnt(3)
	global_store_dwordx4 v[206:207], v[16:19], off
	s_waitcnt lgkmcnt(2)
	global_store_dwordx4 v[208:209], v[20:23], off
	s_nop 1
	v_lshl_add_u64 v[206:207], v[206:207], 0, s[38:39]
	v_lshl_add_u64 v[208:209], v[208:209], 0, s[38:39]
	s_waitcnt lgkmcnt(1)
	global_store_dwordx4 v[206:207], v[24:27], off
	s_waitcnt lgkmcnt(0)
	global_store_dwordx4 v[208:209], v[28:31], off
	s_barrier
	s_cbranch_scc1 .LBB0_620
